# MLA loop: K/V prefetch addresses via scalar base + per-lane offset (no per-tile address VALU), LDS prefetch distance 5
# speedup vs baseline: 1.0177x; 1.0049x over previous
.Lmf_pre:
	v_max3_f32 v1, v66, v67, v68
	v_max3_f32 v170, v69, v70, v71
	v_max3_f32 v1, v1, v72, v73
	v_max3_f32 v170, v170, v74, v75
	v_max3_f32 v1, v1, v76, v77
	v_max3_f32 v170, v170, v78, v79
	v_max3_f32 v1, v1, v80, v81
	v_max3_f32 v170, v170, v82, v83
	v_max3_f32 v1, v1, v84, v85
	v_max3_f32 v170, v170, v86, v87
	v_max3_f32 v1, v1, v88, v89
	v_max3_f32 v170, v170, v90, v91
	v_max3_f32 v1, v1, v92, v93
	v_max3_f32 v170, v170, v94, v95
	v_max3_f32 v1, v1, v96, v97
	v_max_f32_e32 v1, v1, v170
	v_mov_b32_e32 v170, v1
	v_mov_b32_e32 v239, 0xc000
	v_cndmask_b32_e64 v238, v239, 0, s[40:41]
	v_permlane32_swap_b32_e32 v1, v170
	v_add_u32_e32 v238, v229, v238
	v_max_f32_e32 v1, v1, v170
	v_mov_b32_e32 v202, v1
	v_sub_f32_e32 v66, v66, v1
	v_sub_f32_e32 v67, v67, v1
	v_sub_f32_e32 v68, v68, v1
	v_sub_f32_e32 v69, v69, v1
	v_sub_f32_e32 v70, v70, v1
	v_sub_f32_e32 v71, v71, v1
	v_sub_f32_e32 v72, v72, v1
	v_sub_f32_e32 v73, v73, v1
	v_sub_f32_e32 v74, v74, v1
	v_sub_f32_e32 v75, v75, v1
	v_sub_f32_e32 v76, v76, v1
	v_sub_f32_e32 v77, v77, v1
	v_sub_f32_e32 v78, v78, v1
	v_sub_f32_e32 v79, v79, v1
	v_sub_f32_e32 v80, v80, v1
	v_sub_f32_e32 v81, v81, v1
	v_sub_f32_e32 v82, v82, v1
	v_sub_f32_e32 v83, v83, v1
	v_sub_f32_e32 v84, v84, v1
	v_sub_f32_e32 v85, v85, v1
	v_sub_f32_e32 v86, v86, v1
	v_sub_f32_e32 v87, v87, v1
	v_sub_f32_e32 v88, v88, v1
	v_sub_f32_e32 v89, v89, v1
	v_sub_f32_e32 v90, v90, v1
	v_sub_f32_e32 v91, v91, v1
	v_sub_f32_e32 v92, v92, v1
	v_sub_f32_e32 v93, v93, v1
	v_sub_f32_e32 v94, v94, v1
	v_sub_f32_e32 v95, v95, v1
	v_sub_f32_e32 v96, v96, v1
	v_sub_f32_e32 v97, v97, v1
	v_sub_f32_e32 v146, 0, v1
	v_sub_f32_e32 v147, 0, v1
	v_sub_f32_e32 v148, 0, v1
	v_sub_f32_e32 v149, 0, v1
	v_sub_f32_e32 v150, 0, v1
	v_sub_f32_e32 v151, 0, v1
	v_sub_f32_e32 v152, 0, v1
	v_sub_f32_e32 v153, 0, v1
	v_sub_f32_e32 v154, 0, v1
	v_sub_f32_e32 v155, 0, v1
	v_sub_f32_e32 v156, 0, v1
	v_sub_f32_e32 v157, 0, v1
	v_sub_f32_e32 v158, 0, v1
	v_sub_f32_e32 v159, 0, v1
	v_sub_f32_e32 v160, 0, v1
	v_sub_f32_e32 v161, 0, v1
	v_subrev_u32_e32 v235, s2, v204
	v_subrev_u32_e32 v236, s2, v206
	v_subrev_u32_e32 v237, s4, v200
	v_mad_u32_u24 v235, v226, s90, v235
	v_mad_u32_u24 v236, v227, s90, v236
	s_add_u32 s14, s2, 0x48000
	s_addc_u32 s15, s3, 0
	s_add_u32 s12, s4, 0x100
	s_addc_u32 s13, s5, 0
	v_cndmask_b32_e64 v236, v235, v236, s[40:41]
.Lmf_loop:
	ds_read_b128 v[162:165], v216 offset:13312
	ds_read_b128 v[166:169], v216 offset:19968
	ds_read_b128 v[172:175], v216 offset:13344
	ds_read_b128 v[176:179], v216 offset:20000
	ds_read_b128 v[180:183], v216 offset:13376
	global_load_dwordx4 v[130:133], v235, s[14:15]
	global_load_dwordx4 v[134:137], v236, s[14:15]
	s_add_u32 s14, s14, 0x18000
	s_addc_u32 s15, s15, 0
	global_load_dwordx4 v[142:145], v237, s[12:13]
	s_add_u32 s12, s12, 0x80
	s_addc_u32 s13, s13, 0
	v_exp_f32_e32 v66, v66
	v_exp_f32_e32 v67, v67
	v_exp_f32_e32 v68, v68
	v_exp_f32_e32 v69, v69
	s_waitcnt lgkmcnt(4)
	v_mfma_f32_32x32x16_bf16 v[34:49], v[162:165], v[98:101], v[146:161]
	ds_read_b128 v[184:187], v216 offset:20032
	v_add_f32_e32 v171, v66, v171
	v_exp_f32_e32 v70, v70
	v_exp_f32_e32 v71, v71
	s_waitcnt lgkmcnt(4)
	v_mfma_f32_32x32x16_bf16 v[50:65], v[166:169], v[98:101], v[146:161]
	ds_read_b128 v[188:191], v216 offset:13408
	v_add_f32_e32 v171, v68, v171
	v_exp_f32_e32 v72, v72
	v_add_f32_e32 v197, v67, v69
	v_exp_f32_e32 v73, v73
	s_waitcnt lgkmcnt(4)
	v_mfma_f32_32x32x16_bf16 v[34:49], v[172:175], v[102:105], v[34:49]
	ds_read_b128 v[192:195], v216 offset:20064
	v_add_f32_e32 v171, v70, v171
	v_add_f32_e32 v197, v71, v197
	v_cvt_pk_bf16_f32 v66, v66, v67
	v_add_f32_e32 v171, v72, v171
	v_cvt_pk_bf16_f32 v67, v68, v69
	v_add_f32_e32 v197, v73, v197
	v_cvt_pk_bf16_f32 v68, v70, v71
	s_waitcnt lgkmcnt(4)
	v_mfma_f32_32x32x16_bf16 v[50:65], v[176:179], v[102:105], v[50:65]
	ds_read_b128 v[162:165], v216 offset:13440
	v_cvt_pk_bf16_f32 v69, v72, v73
	v_exp_f32_e32 v74, v74
	v_exp_f32_e32 v75, v75
	v_exp_f32_e32 v76, v76
	s_waitcnt lgkmcnt(4)
	v_mfma_f32_32x32x16_bf16 v[34:49], v[180:183], v[106:109], v[34:49]
	ds_read_b128 v[166:169], v216 offset:20096
	v_exp_f32_e32 v77, v77
	v_add_f32_e32 v171, v74, v171
	v_exp_f32_e32 v78, v78
	s_waitcnt lgkmcnt(4)
	v_mfma_f32_32x32x16_bf16 v[50:65], v[184:187], v[106:109], v[50:65]
	ds_read_b128 v[172:175], v216 offset:13472
	v_add_f32_e32 v197, v75, v197
	v_exp_f32_e32 v79, v79
	v_add_f32_e32 v171, v76, v171
	v_exp_f32_e32 v80, v80
	s_waitcnt lgkmcnt(4)
	v_mfma_f32_32x32x16_bf16 v[34:49], v[188:191], v[110:113], v[34:49]
	ds_read_b128 v[176:179], v216 offset:20128
	v_add_f32_e32 v197, v77, v197
	v_exp_f32_e32 v81, v81
	v_add_f32_e32 v171, v78, v171
	v_add_f32_e32 v197, v79, v197
	v_cvt_pk_bf16_f32 v74, v74, v75
	v_add_f32_e32 v171, v80, v171
	s_waitcnt lgkmcnt(4)
	v_mfma_f32_32x32x16_bf16 v[50:65], v[192:195], v[110:113], v[50:65]
	ds_read_b128 v[180:183], v217 offset:26624
	v_cvt_pk_bf16_f32 v75, v76, v77
	v_add_f32_e32 v197, v81, v197
	v_cvt_pk_bf16_f32 v76, v78, v79
	v_cvt_pk_bf16_f32 v77, v80, v81
	v_exp_f32_e32 v82, v82
	s_waitcnt lgkmcnt(4)
	v_mfma_f32_32x32x16_bf16 v[34:49], v[162:165], v[114:117], v[34:49]
	ds_read_b128 v[184:187], v217 offset:31232
	v_exp_f32_e32 v83, v83
	v_exp_f32_e32 v84, v84
	v_exp_f32_e32 v85, v85
	s_waitcnt lgkmcnt(4)
	v_mfma_f32_32x32x16_bf16 v[50:65], v[166:169], v[114:117], v[50:65]
	ds_read_b128 v[188:191], v217 offset:26656
	v_add_f32_e32 v171, v82, v171
	v_exp_f32_e32 v86, v86
	v_add_f32_e32 v197, v83, v197
	v_exp_f32_e32 v87, v87
	s_waitcnt lgkmcnt(4)
	v_mfma_f32_32x32x16_bf16 v[34:49], v[172:175], v[118:121], v[34:49]
	ds_read_b128 v[192:195], v217 offset:31264
	v_add_f32_e32 v171, v84, v171
	v_exp_f32_e32 v88, v88
	v_add_f32_e32 v197, v85, v197
	v_exp_f32_e32 v89, v89
	v_add_f32_e32 v171, v86, v171
	s_waitcnt lgkmcnt(4)
	v_mfma_f32_32x32x16_bf16 v[50:65], v[176:179], v[118:121], v[50:65]
	ds_read_b128 v[162:165], v217 offset:26688
	v_add_f32_e32 v197, v87, v197
	v_cvt_pk_bf16_f32 v82, v82, v83
	v_add_f32_e32 v171, v88, v171
	v_cvt_pk_bf16_f32 v83, v84, v85
	v_add_f32_e32 v197, v89, v197
	v_cvt_pk_bf16_f32 v84, v86, v87
	s_waitcnt lgkmcnt(4)
	v_mfma_f32_32x32x16_bf16 v[18:33], v[180:183], v[66:69], v[18:33]
	ds_read_b128 v[166:169], v217 offset:31296
	v_cvt_pk_bf16_f32 v85, v88, v89
	v_exp_f32_e32 v90, v90
	v_exp_f32_e32 v91, v91
	v_exp_f32_e32 v92, v92
	s_waitcnt lgkmcnt(4)
	v_mfma_f32_32x32x16_bf16 v[2:17], v[184:187], v[66:69], v[2:17]
	ds_read_b128 v[172:175], v217 offset:26720
	v_exp_f32_e32 v93, v93
	v_add_f32_e32 v171, v90, v171
	v_exp_f32_e32 v94, v94
	s_waitcnt lgkmcnt(4)
	v_mfma_f32_32x32x16_bf16 v[18:33], v[188:191], v[74:77], v[18:33]
	ds_read_b128 v[176:179], v217 offset:31328
	v_add_f32_e32 v197, v91, v197
	v_exp_f32_e32 v95, v95
	v_add_f32_e32 v171, v92, v171
	v_exp_f32_e32 v96, v96
	v_add_f32_e32 v197, v93, v197
	s_waitcnt lgkmcnt(4)
	v_mfma_f32_32x32x16_bf16 v[2:17], v[192:195], v[74:77], v[2:17]
	s_waitcnt vmcnt(3)
	v_add_u32_e32 v196, 0x8800, v215
	ds_write_b128 v228, v[122:125]
	ds_write_b128 v238, v[126:129]
	ds_write2_b64 v196, v[138:139], v[140:141] offset0:128 offset1:130
	v_exp_f32_e32 v97, v97
	v_add_f32_e32 v171, v94, v171
	v_add_f32_e32 v197, v95, v197
	v_cvt_pk_bf16_f32 v90, v90, v91
	v_add_f32_e32 v171, v96, v171
	s_waitcnt lgkmcnt(6)
	v_mfma_f32_32x32x16_bf16 v[18:33], v[162:165], v[82:85], v[18:33]
	v_cvt_pk_bf16_f32 v91, v92, v93
	v_add_f32_e32 v197, v97, v197
	v_cvt_pk_bf16_f32 v92, v94, v95
	v_cvt_pk_bf16_f32 v93, v96, v97
	v_max3_f32 v1, v34, v35, v36
	v_max3_f32 v170, v37, v38, v39
	s_waitcnt lgkmcnt(5)
	v_mfma_f32_32x32x16_bf16 v[2:17], v[166:169], v[82:85], v[2:17]
	v_max3_f32 v1, v1, v40, v41
	v_max3_f32 v170, v170, v42, v43
	v_max3_f32 v1, v1, v44, v45
	v_max3_f32 v170, v170, v46, v47
	v_max3_f32 v1, v1, v48, v49
	v_max3_f32 v170, v170, v50, v51
	s_waitcnt lgkmcnt(4)
	v_mfma_f32_32x32x16_bf16 v[18:33], v[172:175], v[90:93], v[18:33]
	v_max3_f32 v1, v1, v52, v53
	v_max3_f32 v170, v170, v54, v55
	v_max3_f32 v1, v1, v56, v57
	v_max3_f32 v170, v170, v58, v59
	v_max3_f32 v1, v1, v60, v61
	v_max3_f32 v170, v170, v62, v63
	v_max3_f32 v1, v1, v64, v65
	s_waitcnt lgkmcnt(3)
	v_mfma_f32_32x32x16_bf16 v[2:17], v[176:179], v[90:93], v[2:17]
	v_max_f32_e32 v1, v1, v170
	v_mov_b32_e32 v170, v1
	v_add_f32_e32 v171, v197, v171
	s_nop 0
	v_permlane32_swap_b32_e32 v1, v170
	v_max_f32_e32 v1, v1, v170
	v_cmp_lt_f32_e32 vcc, s93, v1
	s_cbranch_vccnz .Lmf_slow_0
.Lmf_join_0:
	s_waitcnt lgkmcnt(0)
	s_barrier
	ds_read_b128 v[162:165], v216 offset:0
	ds_read_b128 v[166:169], v216 offset:6656
	ds_read_b128 v[172:175], v216 offset:32
	ds_read_b128 v[176:179], v216 offset:6688
	ds_read_b128 v[180:183], v216 offset:64
	global_load_dwordx4 v[122:125], v235, s[14:15]
	global_load_dwordx4 v[126:129], v236, s[14:15]
	s_add_u32 s14, s14, 0x18000
	s_addc_u32 s15, s15, 0
	global_load_dwordx4 v[138:141], v237, s[12:13]
	s_add_u32 s12, s12, 0x80
	s_addc_u32 s13, s13, 0
	v_exp_f32_e32 v34, v34
	v_exp_f32_e32 v35, v35
	v_exp_f32_e32 v36, v36
	v_exp_f32_e32 v37, v37
	s_waitcnt lgkmcnt(4)
	v_mfma_f32_32x32x16_bf16 v[66:81], v[162:165], v[98:101], v[146:161]
	ds_read_b128 v[184:187], v216 offset:6720
	v_add_f32_e32 v171, v34, v171
	v_exp_f32_e32 v38, v38
	v_exp_f32_e32 v39, v39
	s_waitcnt lgkmcnt(4)
	v_mfma_f32_32x32x16_bf16 v[82:97], v[166:169], v[98:101], v[146:161]
	ds_read_b128 v[188:191], v216 offset:96
	v_add_f32_e32 v171, v36, v171
	v_exp_f32_e32 v40, v40
	v_add_f32_e32 v197, v35, v37
	v_exp_f32_e32 v41, v41
	s_waitcnt lgkmcnt(4)
	v_mfma_f32_32x32x16_bf16 v[66:81], v[172:175], v[102:105], v[66:81]
	ds_read_b128 v[192:195], v216 offset:6752
	v_add_f32_e32 v171, v38, v171
	v_add_f32_e32 v197, v39, v197
	v_cvt_pk_bf16_f32 v34, v34, v35
	v_add_f32_e32 v171, v40, v171
	v_cvt_pk_bf16_f32 v35, v36, v37
	v_add_f32_e32 v197, v41, v197
	v_cvt_pk_bf16_f32 v36, v38, v39
	s_waitcnt lgkmcnt(4)
	v_mfma_f32_32x32x16_bf16 v[82:97], v[176:179], v[102:105], v[82:97]
	ds_read_b128 v[162:165], v216 offset:128
	v_cvt_pk_bf16_f32 v37, v40, v41
	v_exp_f32_e32 v42, v42
	v_exp_f32_e32 v43, v43
	v_exp_f32_e32 v44, v44
	s_waitcnt lgkmcnt(4)
	v_mfma_f32_32x32x16_bf16 v[66:81], v[180:183], v[106:109], v[66:81]
	ds_read_b128 v[166:169], v216 offset:6784
	v_exp_f32_e32 v45, v45
	v_add_f32_e32 v171, v42, v171
	v_exp_f32_e32 v46, v46
	s_waitcnt lgkmcnt(4)
	v_mfma_f32_32x32x16_bf16 v[82:97], v[184:187], v[106:109], v[82:97]
	ds_read_b128 v[172:175], v216 offset:160
	v_add_f32_e32 v197, v43, v197
	v_exp_f32_e32 v47, v47
	v_add_f32_e32 v171, v44, v171
	v_exp_f32_e32 v48, v48
	s_waitcnt lgkmcnt(4)
	v_mfma_f32_32x32x16_bf16 v[66:81], v[188:191], v[110:113], v[66:81]
	ds_read_b128 v[176:179], v216 offset:6816
	v_add_f32_e32 v197, v45, v197
	v_exp_f32_e32 v49, v49
	v_add_f32_e32 v171, v46, v171
	v_add_f32_e32 v197, v47, v197
	v_cvt_pk_bf16_f32 v42, v42, v43
	v_add_f32_e32 v171, v48, v171
	s_waitcnt lgkmcnt(4)
	v_mfma_f32_32x32x16_bf16 v[82:97], v[192:195], v[110:113], v[82:97]
	ds_read_b128 v[180:183], v217 offset:35840
	v_cvt_pk_bf16_f32 v43, v44, v45
	v_add_f32_e32 v197, v49, v197
	v_cvt_pk_bf16_f32 v44, v46, v47
	v_cvt_pk_bf16_f32 v45, v48, v49
	v_exp_f32_e32 v50, v50
	s_waitcnt lgkmcnt(4)
	v_mfma_f32_32x32x16_bf16 v[66:81], v[162:165], v[114:117], v[66:81]
	ds_read_b128 v[184:187], v217 offset:40448
	v_exp_f32_e32 v51, v51
	v_exp_f32_e32 v52, v52
	v_exp_f32_e32 v53, v53
	s_waitcnt lgkmcnt(4)
	v_mfma_f32_32x32x16_bf16 v[82:97], v[166:169], v[114:117], v[82:97]
	ds_read_b128 v[188:191], v217 offset:35872
	v_add_f32_e32 v171, v50, v171
	v_exp_f32_e32 v54, v54
	v_add_f32_e32 v197, v51, v197
	v_exp_f32_e32 v55, v55
	s_waitcnt lgkmcnt(4)
	v_mfma_f32_32x32x16_bf16 v[66:81], v[172:175], v[118:121], v[66:81]
	ds_read_b128 v[192:195], v217 offset:40480
	v_add_f32_e32 v171, v52, v171
	v_exp_f32_e32 v56, v56
	v_add_f32_e32 v197, v53, v197
	v_exp_f32_e32 v57, v57
	v_add_f32_e32 v171, v54, v171
	s_waitcnt lgkmcnt(4)
	v_mfma_f32_32x32x16_bf16 v[82:97], v[176:179], v[118:121], v[82:97]
	ds_read_b128 v[162:165], v217 offset:35904
	v_add_f32_e32 v197, v55, v197
	v_cvt_pk_bf16_f32 v50, v50, v51
	v_add_f32_e32 v171, v56, v171
	v_cvt_pk_bf16_f32 v51, v52, v53
	v_add_f32_e32 v197, v57, v197
	v_cvt_pk_bf16_f32 v52, v54, v55
	s_waitcnt lgkmcnt(4)
	v_mfma_f32_32x32x16_bf16 v[18:33], v[180:183], v[34:37], v[18:33]
	ds_read_b128 v[166:169], v217 offset:40512
	v_cvt_pk_bf16_f32 v53, v56, v57
	v_exp_f32_e32 v58, v58
	v_exp_f32_e32 v59, v59
	v_exp_f32_e32 v60, v60
	s_waitcnt lgkmcnt(4)
	v_mfma_f32_32x32x16_bf16 v[2:17], v[184:187], v[34:37], v[2:17]
	ds_read_b128 v[172:175], v217 offset:35936
	v_exp_f32_e32 v61, v61
	v_add_f32_e32 v171, v58, v171
	v_exp_f32_e32 v62, v62
	s_waitcnt lgkmcnt(4)
	v_mfma_f32_32x32x16_bf16 v[18:33], v[188:191], v[42:45], v[18:33]
	ds_read_b128 v[176:179], v217 offset:40544
	v_add_f32_e32 v197, v59, v197
	v_exp_f32_e32 v63, v63
	v_add_f32_e32 v171, v60, v171
	v_exp_f32_e32 v64, v64
	v_add_f32_e32 v197, v61, v197
	s_waitcnt lgkmcnt(4)
	v_mfma_f32_32x32x16_bf16 v[2:17], v[192:195], v[42:45], v[2:17]
	s_waitcnt vmcnt(3)
	ds_write_b128 v228, v[130:133] offset:13312
	ds_write_b128 v238, v[134:137] offset:13312
	ds_write2_b64 v225, v[142:143], v[144:145] offset1:2
	v_exp_f32_e32 v65, v65
	v_add_f32_e32 v171, v62, v171
	v_add_f32_e32 v197, v63, v197
	v_cvt_pk_bf16_f32 v58, v58, v59
	v_add_f32_e32 v171, v64, v171
	s_waitcnt lgkmcnt(6)
	v_mfma_f32_32x32x16_bf16 v[18:33], v[162:165], v[50:53], v[18:33]
	v_cvt_pk_bf16_f32 v59, v60, v61
	v_add_f32_e32 v197, v65, v197
	v_cvt_pk_bf16_f32 v60, v62, v63
	v_cvt_pk_bf16_f32 v61, v64, v65
	v_max3_f32 v1, v66, v67, v68
	v_max3_f32 v170, v69, v70, v71
	s_waitcnt lgkmcnt(5)
	v_mfma_f32_32x32x16_bf16 v[2:17], v[166:169], v[50:53], v[2:17]
	v_max3_f32 v1, v1, v72, v73
	v_max3_f32 v170, v170, v74, v75
	v_max3_f32 v1, v1, v76, v77
	v_max3_f32 v170, v170, v78, v79
	v_max3_f32 v1, v1, v80, v81
	v_max3_f32 v170, v170, v82, v83
	s_waitcnt lgkmcnt(4)
	v_mfma_f32_32x32x16_bf16 v[18:33], v[172:175], v[58:61], v[18:33]
	v_max3_f32 v1, v1, v84, v85
	v_max3_f32 v170, v170, v86, v87
	v_max3_f32 v1, v1, v88, v89
	v_max3_f32 v170, v170, v90, v91
	v_max3_f32 v1, v1, v92, v93
	v_max3_f32 v170, v170, v94, v95
	v_max3_f32 v1, v1, v96, v97
	s_waitcnt lgkmcnt(3)
	v_mfma_f32_32x32x16_bf16 v[2:17], v[176:179], v[58:61], v[2:17]
	v_max_f32_e32 v1, v1, v170
	v_mov_b32_e32 v170, v1
	v_add_f32_e32 v171, v197, v171
	s_nop 0
	v_permlane32_swap_b32_e32 v1, v170
	v_max_f32_e32 v1, v1, v170
	v_cmp_lt_f32_e32 vcc, s93, v1
	s_cbranch_vccnz .Lmf_slow_1
.Lmf_join_1:
	s_waitcnt lgkmcnt(0)
	s_barrier
	s_add_i32 s83, s18, 2
	s_add_i32 s84, s18, 3
	s_addk_i32 s19, 0x80
	s_cmp_ge_i32 s84, s17
	s_cbranch_scc1 .Lmf_exit
	s_mov_b32 s18, s83
	s_branch .Lmf_loop
